# stack: pipelined sample mLSTM loop + hand-written 16-in-flight kv copies + shortened grid-barrier release chain
# baseline (speedup 1.0000x reference)
; #define LAS __attribute__((address_space(3)))
; __device__ __forceinline__ float exp_(float x) { return __builtin_amdgcn_exp2f(x * LOG2E); }
; __device__ __forceinline__ void sample_mlstm_unit(const Params& P, LAS unsigned char* lds, int unit) {
;     ...
;     const float* GT = (const float*)(ws + WS_GATES) + row * 8;
;     const float ig = GT[h], lf = GT[4 + h], m0 = P.in[8][b * 4 + h];
;     const float a = ig - lf, M = fmaxf(m0, a), m_new = lf + M, wk = exp_(a - M), decay = exp_(m0 - M);
;     const float* n0 = P.in[7] + (size_t)(b * 4 + h) * 256;
;     __syncthreads();
;     float qk = 0.f, qn = 0.f;
; #pragma unroll
;     for (int c = 0; c < 4; ++c) { const int j = lane + 64 * c; qk += qS[j] * kS[j]; qn += qS[j] * n0[j]; }
;     qk = wave_sum(qk); qn = wave_sum(qn);
;     {
;         const float* C0 = P.in[6] + (size_t)(b * 4 + h) * 65536; float* C1 = P.out + O_C_S + (size_t)(b * 4 + h) * 65536;
;         const int c4 = lane * 4;
;         const f32x4v v4 = *(const LAS f32x4v*)(vS + c4);
;         f32x4v acc = (f32x4v){0.f, 0.f, 0.f, 0.f};
; #pragma unroll 4
;         for (int r = 0; r < 32; ++r) {
;             const int dk = w * 32 + r;
;             const f32x4v c0 = *(const f32x4v*)(C0 + (size_t)dk * 256 + c4);
;             acc = acc + c0 * qS[dk];
;             *(f32x4v*)(C1 + (size_t)dk * 256 + c4) = c0 * decay + v4 * (wk * kS[dk]);
.LBB0_566:
	s_or_b64 exec, exec, s[42:43]
	s_lshl_b64 s[34:35], s[40:41], 5
	v_readlane_b32 s15, v253, 19
	s_add_u32 s34, s15, s34
	v_readlane_b32 s15, v252, 62
	s_addc_u32 s35, s15, s35
	s_lshl_b32 s15, s49, 2
	v_mov_b32_e32 v0, s15
	s_ashr_i32 s15, s14, 31
	global_load_dword v1, v0, s[34:35]
	global_load_dword v21, v0, s[34:35] offset:16
	s_lshl_b64 s[34:35], s[14:15], 2
	v_readlane_b32 s40, v255, 43
	v_readlane_b32 s41, v255, 44
	s_add_u32 s34, s40, s34
	v_readlane_b32 s44, v254, 61
	s_addc_u32 s35, s41, s35
	v_readlane_b32 s46, v254, 63
	v_readlane_b32 s47, v255, 0
	global_load_dword v14, v145, s[34:35]
	s_lshl_b64 s[40:41], s[14:15], 8
	s_lshl_b64 s[34:35], s[14:15], 10
	s_mov_b64 s[42:43], s[46:47]
	v_and_b32_e32 v9, 63, v8
	s_add_u32 s42, s42, s34
	s_addc_u32 s43, s43, s35
	v_lshlrev_b32_e32 v3, 2, v9
	s_waitcnt lgkmcnt(0)
	s_barrier
	global_load_dword v15, v3, s[42:43]
	global_load_dword v16, v3, s[42:43] offset:256
	global_load_dword v17, v3, s[42:43] offset:512
	global_load_dword v25, v3, s[42:43] offset:768
	v_and_b32_e32 v2, 64, v178
	v_xor_b32_e32 v4, 1, v178
	v_add_u32_e32 v26, 64, v2
	v_add_u32_e32 v28, 0, v3
	v_cmp_lt_i32_e32 vcc, v4, v26
	v_xor_b32_e32 v19, 2, v178
	v_xor_b32_e32 v20, 4, v178
	v_cndmask_b32_e32 v3, v178, v4, vcc
	ds_read2st64_b32 v[4:5], v28 offset1:1
	ds_read2st64_b32 v[6:7], v28 offset0:4 offset1:5
	ds_read2st64_b32 v[10:11], v28 offset0:6 offset1:7
	ds_read2st64_b32 v[12:13], v28 offset0:2 offset1:3
	v_cmp_lt_i32_e32 vcc, v19, v26
	v_xor_b32_e32 v22, 8, v178
	v_xor_b32_e32 v23, 16, v178
	v_cndmask_b32_e32 v24, v178, v19, vcc
	v_lshlrev_b32_e32 v19, 2, v3
	s_waitcnt lgkmcnt(2)
	v_fma_f32 v3, v4, v6, 0
	v_fmac_f32_e32 v3, v5, v7
	s_waitcnt lgkmcnt(0)
	v_fmac_f32_e32 v3, v12, v10
	v_fmac_f32_e32 v3, v13, v11
	ds_bpermute_b32 v6, v19, v3
	v_cmp_lt_i32_e32 vcc, v20, v26
	v_ashrrev_i32_e32 v18, 6, v8
	v_lshlrev_b32_e32 v2, 5, v18
	v_cndmask_b32_e32 v7, v178, v20, vcc
	v_lshlrev_b32_e32 v20, 2, v24
	s_waitcnt lgkmcnt(0)
	v_add_f32_e32 v6, v3, v6
	ds_bpermute_b32 v11, v20, v6
	v_cmp_lt_i32_e32 vcc, v22, v26
	v_ashrrev_i32_e32 v3, 31, v2
	v_lshlrev_b64 v[2:3], 10, v[2:3]
	v_cndmask_b32_e32 v10, v178, v22, vcc
	v_lshlrev_b32_e32 v22, 2, v7
	s_waitcnt lgkmcnt(0)
	v_add_f32_e32 v6, v6, v11
	ds_bpermute_b32 v7, v22, v6
	v_lshlrev_b32_e32 v24, 2, v10
	v_mad_u32_u24 v10, v9, 12, v28
	v_cmp_lt_i32_e32 vcc, v23, v26
	v_readlane_b32 s45, v254, 62
	s_waitcnt lgkmcnt(0)
	v_add_f32_e32 v11, v6, v7
	ds_bpermute_b32 v28, v24, v11
	v_cndmask_b32_e32 v23, v178, v23, vcc
	v_lshlrev_b32_e32 v23, 2, v23
	v_mov_b32_e32 v0, 0
	v_lshl_or_b32 v2, v9, 4, v2
	s_waitcnt lgkmcnt(0)
	v_add_f32_e32 v29, v11, v28
	ds_bpermute_b32 v30, v23, v29
	v_lshl_add_u32 v27, v18, 7, 0
	s_mov_b64 s[44:45], 0
	s_waitcnt vmcnt(5)
	v_sub_f32_e32 v1, v1, v21
	s_waitcnt vmcnt(3)
	v_fma_f32 v15, v4, v15, 0
	s_waitcnt vmcnt(2)
	v_fmac_f32_e32 v15, v5, v16
	s_waitcnt vmcnt(1)
	v_fmac_f32_e32 v15, v12, v17
	s_waitcnt vmcnt(0)
	v_fmac_f32_e32 v15, v13, v25
	ds_bpermute_b32 v16, v19, v15
	ds_read_b128 v[4:7], v10 offset:2048
	v_lshl_add_u64 v[12:13], s[8:9], 0, v[2:3]
	s_waitcnt lgkmcnt(1)
	v_add_f32_e32 v10, v15, v16
	ds_bpermute_b32 v11, v20, v10
	v_max_f32_e32 v15, v14, v14
	v_max_f32_e32 v28, v15, v1
	v_sub_f32_e32 v1, v1, v28
	v_mul_f32_e32 v1, 0x3fb8aa3b, v1
	s_waitcnt lgkmcnt(0)
	v_add_f32_e32 v11, v10, v11
	ds_bpermute_b32 v15, v22, v11
	v_sub_f32_e32 v10, v14, v28
	v_mul_f32_e32 v10, 0x3fb8aa3b, v10
	v_exp_f32_e32 v10, v10
	v_exp_f32_e32 v25, v1
	s_waitcnt lgkmcnt(0)
	v_add_f32_e32 v11, v11, v15
	ds_bpermute_b32 v16, v24, v11
	v_mov_b32_e32 v14, v10
	v_mov_b32_e32 v15, v10
	v_mov_b32_e32 v1, v0
	s_waitcnt lgkmcnt(0)
	v_add_f32_e32 v31, v11, v16
	ds_bpermute_b32 v32, v23, v31
	v_lshl_add_u64 v[16:17], s[6:7], 0, v[2:3]
	v_mov_b32_e32 v2, v0
	v_mov_b32_e32 v3, v0
	s_mov_b32 s99, 0
	s_mov_b32 s98, 0x0
	v_lshl_add_u64 v[46:47], v[16:17], 0, s[98:99]
	global_load_dwordx4 v[96:99], v[46:47], off
	global_load_dwordx4 v[100:103], v[46:47], off offset:1024
	global_load_dwordx4 v[104:107], v[46:47], off offset:2048
	global_load_dwordx4 v[108:111], v[46:47], off offset:3072
	s_mov_b32 s98, 0x1000
	v_lshl_add_u64 v[46:47], v[16:17], 0, s[98:99]
	global_load_dwordx4 v[112:115], v[46:47], off
	global_load_dwordx4 v[116:119], v[46:47], off offset:1024
	global_load_dwordx4 v[120:123], v[46:47], off offset:2048
	global_load_dwordx4 v[124:127], v[46:47], off offset:3072
	s_mov_b32 s98, 0x2000
	v_lshl_add_u64 v[46:47], v[16:17], 0, s[98:99]
	global_load_dwordx4 v[128:131], v[46:47], off
	global_load_dwordx4 v[132:135], v[46:47], off offset:1024
	global_load_dwordx4 v[136:139], v[46:47], off offset:2048
	global_load_dwordx4 v[140:143], v[46:47], off offset:3072
	s_mov_b32 s98, 0x3000
	v_lshl_add_u64 v[46:47], v[16:17], 0, s[98:99]
	global_load_dwordx4 v[146:149], v[46:47], off
	global_load_dwordx4 v[150:153], v[46:47], off offset:1024
	global_load_dwordx4 v[154:157], v[46:47], off offset:2048
	global_load_dwordx4 v[158:161], v[46:47], off offset:3072
	s_mov_b32 s98, 0x4000
	v_lshl_add_u64 v[46:47], v[16:17], 0, s[98:99]
	global_load_dwordx4 v[162:165], v[46:47], off
	global_load_dwordx4 v[166:169], v[46:47], off offset:1024
	global_load_dwordx4 v[170:173], v[46:47], off offset:2048
	global_load_dwordx4 v[174:177], v[46:47], off offset:3072
	s_mov_b32 s98, 0x5000
	v_lshl_add_u64 v[46:47], v[16:17], 0, s[98:99]
	global_load_dwordx4 v[180:183], v[46:47], off
	global_load_dwordx4 v[184:187], v[46:47], off offset:1024
	global_load_dwordx4 v[188:191], v[46:47], off offset:2048
	global_load_dwordx4 v[192:195], v[46:47], off offset:3072
	s_mov_b32 s98, 0x6000
	v_lshl_add_u64 v[46:47], v[16:17], 0, s[98:99]
	global_load_dwordx4 v[196:199], v[46:47], off
	global_load_dwordx4 v[200:203], v[46:47], off offset:1024
	global_load_dwordx4 v[204:207], v[46:47], off offset:2048
	global_load_dwordx4 v[208:211], v[46:47], off offset:3072
	s_mov_b32 s98, 0x7000
	v_lshl_add_u64 v[46:47], v[16:17], 0, s[98:99]
	global_load_dwordx4 v[212:215], v[46:47], off
	global_load_dwordx4 v[216:219], v[46:47], off offset:1024
	global_load_dwordx4 v[220:223], v[46:47], off offset:2048
	global_load_dwordx4 v[224:227], v[46:47], off offset:3072
; __device__ __forceinline__ void sample_mlstm_unit(const Params& P, LAS unsigned char* lds, int unit) {
;     ...
; #pragma unroll 4
;         for (int r = 0; r < 32; ++r) {
;             const int dk = w * 32 + r;
;             const f32x4v c0 = *(const f32x4v*)(C0 + (size_t)dk * 256 + c4);
;             acc = acc + c0 * qS[dk];
;             *(f32x4v*)(C1 + (size_t)dk * 256 + c4) = c0 * decay + v4 * (wk * kS[dk]);
;         }
.LBB0_567:
	v_lshl_add_u64 v[46:47], v[16:17], 0, s[44:45]
	s_nop 0
	ds_read_b128 v[38:41], v27
	ds_read_b128 v[42:45], v27 offset:1024
	v_mov_b32_e32 v11, v10
	v_lshl_add_u64 v[52:53], v[12:13], 0, s[44:45]
	s_add_u32 s44, s44, 0x1000
	s_addc_u32 s45, s45, 0
	v_add_u32_e32 v27, 16, v27
	s_cmpk_eq_u32 s44, 0x8000
	s_waitcnt vmcnt(31) lgkmcnt(1)
	v_pk_fma_f32 v[48:49], v[96:97], v[38:39], v[0:1] op_sel_hi:[1,0,1]
	s_waitcnt lgkmcnt(0)
	v_mul_f32_e32 v0, v25, v42
	v_pk_fma_f32 v[50:51], v[98:99], v[38:39], v[2:3] op_sel_hi:[1,0,1]
	v_pk_mul_f32 v[2:3], v[6:7], v[0:1] op_sel_hi:[1,0]
	v_pk_mul_f32 v[0:1], v[4:5], v[0:1] op_sel_hi:[1,0]
	v_pk_fma_f32 v[2:3], v[10:11], v[98:99], v[2:3]
	v_pk_fma_f32 v[0:1], v[14:15], v[96:97], v[0:1]
	global_store_dwordx4 v[52:53], v[0:3], off offset:-2048
	s_nop 0
	s_waitcnt vmcnt(31)
	v_pk_fma_f32 v[96:97], v[102:103], v[38:39], v[50:51] op_sel:[0,1,0]
	v_pk_fma_f32 v[98:99], v[100:101], v[38:39], v[48:49] op_sel:[0,1,0]
	v_mul_f32_e32 v38, v25, v43
	v_pk_mul_f32 v[42:43], v[6:7], v[38:39] op_sel_hi:[1,0]
	v_pk_mul_f32 v[38:39], v[4:5], v[38:39] op_sel_hi:[1,0]
	v_pk_fma_f32 v[102:103], v[10:11], v[102:103], v[42:43]
	v_pk_fma_f32 v[100:101], v[14:15], v[100:101], v[38:39]
	global_store_dwordx4 v[52:53], v[100:103], off offset:-1024
	s_nop 0
	s_waitcnt vmcnt(31)
	v_pk_fma_f32 v[38:39], v[106:107], v[40:41], v[96:97] op_sel_hi:[1,0,1]
	v_mul_f32_e32 v96, v25, v44
	v_pk_fma_f32 v[42:43], v[104:105], v[40:41], v[98:99] op_sel_hi:[1,0,1]
	v_pk_mul_f32 v[98:99], v[6:7], v[96:97] op_sel_hi:[1,0]
	v_pk_mul_f32 v[96:97], v[4:5], v[96:97] op_sel_hi:[1,0]
	v_pk_fma_f32 v[106:107], v[10:11], v[106:107], v[98:99]
	v_pk_fma_f32 v[104:105], v[14:15], v[104:105], v[96:97]
	global_store_dwordx4 v[52:53], v[104:107], off
	s_nop 0
	s_nop 0
	v_mov_b32_e32 v104, v41
	s_waitcnt vmcnt(31)
	v_pk_fma_f32 v[106:107], v[110:111], v[104:105], v[38:39] op_sel_hi:[1,0,1]
	v_mul_f32_e32 v38, v25, v45
	v_pk_mul_f32 v[40:41], v[6:7], v[38:39] op_sel_hi:[1,0]
	v_pk_mul_f32 v[38:39], v[4:5], v[38:39] op_sel_hi:[1,0]
	v_pk_fma_f32 v[104:105], v[108:109], v[104:105], v[42:43] op_sel_hi:[1,0,1]
	v_pk_fma_f32 v[110:111], v[10:11], v[110:111], v[40:41]
	v_pk_fma_f32 v[108:109], v[14:15], v[108:109], v[38:39]
	global_store_dwordx4 v[52:53], v[108:111], off offset:1024
	v_lshl_add_u64 v[46:47], v[16:17], 0, s[44:45]
	s_nop 0
	ds_read_b128 v[38:41], v27
	ds_read_b128 v[42:45], v27 offset:1024
	v_mov_b32_e32 v11, v10
	v_lshl_add_u64 v[52:53], v[12:13], 0, s[44:45]
	s_add_u32 s44, s44, 0x1000
	s_addc_u32 s45, s45, 0
	v_add_u32_e32 v27, 16, v27
	s_cmpk_eq_u32 s44, 0x8000
	s_waitcnt vmcnt(31) lgkmcnt(1)
	v_pk_fma_f32 v[48:49], v[112:113], v[38:39], v[104:105] op_sel_hi:[1,0,1]
	s_waitcnt lgkmcnt(0)
	v_mul_f32_e32 v104, v25, v42
	v_pk_fma_f32 v[50:51], v[114:115], v[38:39], v[106:107] op_sel_hi:[1,0,1]
	v_pk_mul_f32 v[106:107], v[6:7], v[104:105] op_sel_hi:[1,0]
	v_pk_mul_f32 v[104:105], v[4:5], v[104:105] op_sel_hi:[1,0]
	v_pk_fma_f32 v[106:107], v[10:11], v[114:115], v[106:107]
	v_pk_fma_f32 v[104:105], v[14:15], v[112:113], v[104:105]
	global_store_dwordx4 v[52:53], v[104:107], off offset:-2048
	s_nop 0
	s_waitcnt vmcnt(31)
	v_pk_fma_f32 v[112:113], v[118:119], v[38:39], v[50:51] op_sel:[0,1,0]
	v_pk_fma_f32 v[114:115], v[116:117], v[38:39], v[48:49] op_sel:[0,1,0]
	v_mul_f32_e32 v38, v25, v43
	v_pk_mul_f32 v[42:43], v[6:7], v[38:39] op_sel_hi:[1,0]
	v_pk_mul_f32 v[38:39], v[4:5], v[38:39] op_sel_hi:[1,0]
	v_pk_fma_f32 v[118:119], v[10:11], v[118:119], v[42:43]
	v_pk_fma_f32 v[116:117], v[14:15], v[116:117], v[38:39]
	global_store_dwordx4 v[52:53], v[116:119], off offset:-1024
	s_nop 0
	s_waitcnt vmcnt(31)
	v_pk_fma_f32 v[38:39], v[122:123], v[40:41], v[112:113] op_sel_hi:[1,0,1]
	v_mul_f32_e32 v112, v25, v44
	v_pk_fma_f32 v[42:43], v[120:121], v[40:41], v[114:115] op_sel_hi:[1,0,1]
	v_pk_mul_f32 v[114:115], v[6:7], v[112:113] op_sel_hi:[1,0]
	v_pk_mul_f32 v[112:113], v[4:5], v[112:113] op_sel_hi:[1,0]
	v_pk_fma_f32 v[122:123], v[10:11], v[122:123], v[114:115]
	v_pk_fma_f32 v[120:121], v[14:15], v[120:121], v[112:113]
	global_store_dwordx4 v[52:53], v[120:123], off
	s_nop 0
	s_nop 0
	v_mov_b32_e32 v120, v41
	s_waitcnt vmcnt(31)
	v_pk_fma_f32 v[122:123], v[126:127], v[120:121], v[38:39] op_sel_hi:[1,0,1]
	v_mul_f32_e32 v38, v25, v45
	v_pk_mul_f32 v[40:41], v[6:7], v[38:39] op_sel_hi:[1,0]
	v_pk_mul_f32 v[38:39], v[4:5], v[38:39] op_sel_hi:[1,0]
	v_pk_fma_f32 v[120:121], v[124:125], v[120:121], v[42:43] op_sel_hi:[1,0,1]
	v_pk_fma_f32 v[126:127], v[10:11], v[126:127], v[40:41]
	v_pk_fma_f32 v[124:125], v[14:15], v[124:125], v[38:39]
	global_store_dwordx4 v[52:53], v[124:127], off offset:1024
	v_lshl_add_u64 v[46:47], v[16:17], 0, s[44:45]
	s_nop 0
	ds_read_b128 v[38:41], v27
	ds_read_b128 v[42:45], v27 offset:1024
	v_mov_b32_e32 v11, v10
	v_lshl_add_u64 v[52:53], v[12:13], 0, s[44:45]
	s_add_u32 s44, s44, 0x1000
	s_addc_u32 s45, s45, 0
	v_add_u32_e32 v27, 16, v27
	s_cmpk_eq_u32 s44, 0x8000
	s_waitcnt vmcnt(31) lgkmcnt(1)
	v_pk_fma_f32 v[48:49], v[128:129], v[38:39], v[120:121] op_sel_hi:[1,0,1]
	s_waitcnt lgkmcnt(0)
	v_mul_f32_e32 v120, v25, v42
	v_pk_fma_f32 v[50:51], v[130:131], v[38:39], v[122:123] op_sel_hi:[1,0,1]
	v_pk_mul_f32 v[122:123], v[6:7], v[120:121] op_sel_hi:[1,0]
	v_pk_mul_f32 v[120:121], v[4:5], v[120:121] op_sel_hi:[1,0]
	v_pk_fma_f32 v[122:123], v[10:11], v[130:131], v[122:123]
	v_pk_fma_f32 v[120:121], v[14:15], v[128:129], v[120:121]
	global_store_dwordx4 v[52:53], v[120:123], off offset:-2048
	s_nop 0
	s_waitcnt vmcnt(31)
; __device__ __forceinline__ void sample_mlstm_unit(const Params& P, LAS unsigned char* lds, int unit) {
;     ...
; #pragma unroll 4
;         for (int r = 0; r < 32; ++r) {
;             const int dk = w * 32 + r;
;             const f32x4v c0 = *(const f32x4v*)(C0 + (size_t)dk * 256 + c4);
;             acc = acc + c0 * qS[dk];
;             *(f32x4v*)(C1 + (size_t)dk * 256 + c4) = c0 * decay + v4 * (wk * kS[dk]);
;         }
	v_pk_fma_f32 v[128:129], v[134:135], v[38:39], v[50:51] op_sel:[0,1,0]
	v_pk_fma_f32 v[130:131], v[132:133], v[38:39], v[48:49] op_sel:[0,1,0]
	v_mul_f32_e32 v38, v25, v43
	v_pk_mul_f32 v[42:43], v[6:7], v[38:39] op_sel_hi:[1,0]
	v_pk_mul_f32 v[38:39], v[4:5], v[38:39] op_sel_hi:[1,0]
	v_pk_fma_f32 v[134:135], v[10:11], v[134:135], v[42:43]
	v_pk_fma_f32 v[132:133], v[14:15], v[132:133], v[38:39]
	global_store_dwordx4 v[52:53], v[132:135], off offset:-1024
	s_nop 0
	s_waitcnt vmcnt(31)
	v_pk_fma_f32 v[38:39], v[138:139], v[40:41], v[128:129] op_sel_hi:[1,0,1]
	v_mul_f32_e32 v128, v25, v44
	v_pk_fma_f32 v[42:43], v[136:137], v[40:41], v[130:131] op_sel_hi:[1,0,1]
	v_pk_mul_f32 v[130:131], v[6:7], v[128:129] op_sel_hi:[1,0]
	v_pk_mul_f32 v[128:129], v[4:5], v[128:129] op_sel_hi:[1,0]
	v_pk_fma_f32 v[138:139], v[10:11], v[138:139], v[130:131]
	v_pk_fma_f32 v[136:137], v[14:15], v[136:137], v[128:129]
	global_store_dwordx4 v[52:53], v[136:139], off
	s_nop 0
	s_nop 0
	v_mov_b32_e32 v136, v41
	s_waitcnt vmcnt(31)
	v_pk_fma_f32 v[138:139], v[142:143], v[136:137], v[38:39] op_sel_hi:[1,0,1]
	v_mul_f32_e32 v38, v25, v45
	v_pk_mul_f32 v[40:41], v[6:7], v[38:39] op_sel_hi:[1,0]
	v_pk_mul_f32 v[38:39], v[4:5], v[38:39] op_sel_hi:[1,0]
	v_pk_fma_f32 v[136:137], v[140:141], v[136:137], v[42:43] op_sel_hi:[1,0,1]
	v_pk_fma_f32 v[142:143], v[10:11], v[142:143], v[40:41]
	v_pk_fma_f32 v[140:141], v[14:15], v[140:141], v[38:39]
	global_store_dwordx4 v[52:53], v[140:143], off offset:1024
	v_lshl_add_u64 v[46:47], v[16:17], 0, s[44:45]
	s_nop 0
	ds_read_b128 v[38:41], v27
	ds_read_b128 v[42:45], v27 offset:1024
	v_mov_b32_e32 v11, v10
	v_lshl_add_u64 v[52:53], v[12:13], 0, s[44:45]
	s_add_u32 s44, s44, 0x1000
	s_addc_u32 s45, s45, 0
	v_add_u32_e32 v27, 16, v27
	s_cmpk_eq_u32 s44, 0x8000
	s_waitcnt vmcnt(31) lgkmcnt(1)
	v_pk_fma_f32 v[48:49], v[146:147], v[38:39], v[136:137] op_sel_hi:[1,0,1]
	s_waitcnt lgkmcnt(0)
	v_mul_f32_e32 v136, v25, v42
	v_pk_fma_f32 v[50:51], v[148:149], v[38:39], v[138:139] op_sel_hi:[1,0,1]
	v_pk_mul_f32 v[138:139], v[6:7], v[136:137] op_sel_hi:[1,0]
	v_pk_mul_f32 v[136:137], v[4:5], v[136:137] op_sel_hi:[1,0]
	v_pk_fma_f32 v[138:139], v[10:11], v[148:149], v[138:139]
	v_pk_fma_f32 v[136:137], v[14:15], v[146:147], v[136:137]
	global_store_dwordx4 v[52:53], v[136:139], off offset:-2048
	s_nop 0
	s_waitcnt vmcnt(31)
	v_pk_fma_f32 v[146:147], v[152:153], v[38:39], v[50:51] op_sel:[0,1,0]
	v_pk_fma_f32 v[148:149], v[150:151], v[38:39], v[48:49] op_sel:[0,1,0]
	v_mul_f32_e32 v38, v25, v43
	v_pk_mul_f32 v[42:43], v[6:7], v[38:39] op_sel_hi:[1,0]
	v_pk_mul_f32 v[38:39], v[4:5], v[38:39] op_sel_hi:[1,0]
	v_pk_fma_f32 v[152:153], v[10:11], v[152:153], v[42:43]
	v_pk_fma_f32 v[150:151], v[14:15], v[150:151], v[38:39]
	global_store_dwordx4 v[52:53], v[150:153], off offset:-1024
	s_nop 0
	s_waitcnt vmcnt(31)
	v_pk_fma_f32 v[38:39], v[156:157], v[40:41], v[146:147] op_sel_hi:[1,0,1]
	v_mul_f32_e32 v146, v25, v44
	v_pk_fma_f32 v[42:43], v[154:155], v[40:41], v[148:149] op_sel_hi:[1,0,1]
	v_pk_mul_f32 v[148:149], v[6:7], v[146:147] op_sel_hi:[1,0]
	v_pk_mul_f32 v[146:147], v[4:5], v[146:147] op_sel_hi:[1,0]
	v_pk_fma_f32 v[156:157], v[10:11], v[156:157], v[148:149]
	v_pk_fma_f32 v[154:155], v[14:15], v[154:155], v[146:147]
	global_store_dwordx4 v[52:53], v[154:157], off
	s_nop 0
	s_nop 0
	v_mov_b32_e32 v154, v41
	s_waitcnt vmcnt(31)
	v_pk_fma_f32 v[156:157], v[160:161], v[154:155], v[38:39] op_sel_hi:[1,0,1]
	v_mul_f32_e32 v38, v25, v45
	v_pk_mul_f32 v[40:41], v[6:7], v[38:39] op_sel_hi:[1,0]
	v_pk_mul_f32 v[38:39], v[4:5], v[38:39] op_sel_hi:[1,0]
	v_pk_fma_f32 v[154:155], v[158:159], v[154:155], v[42:43] op_sel_hi:[1,0,1]
	v_pk_fma_f32 v[160:161], v[10:11], v[160:161], v[40:41]
	v_pk_fma_f32 v[158:159], v[14:15], v[158:159], v[38:39]
	global_store_dwordx4 v[52:53], v[158:161], off offset:1024
	v_lshl_add_u64 v[46:47], v[16:17], 0, s[44:45]
	s_nop 0
	ds_read_b128 v[38:41], v27
	ds_read_b128 v[42:45], v27 offset:1024
	v_mov_b32_e32 v11, v10
	v_lshl_add_u64 v[52:53], v[12:13], 0, s[44:45]
	s_add_u32 s44, s44, 0x1000
	s_addc_u32 s45, s45, 0
	v_add_u32_e32 v27, 16, v27
	s_cmpk_eq_u32 s44, 0x8000
	s_waitcnt vmcnt(31) lgkmcnt(1)
	v_pk_fma_f32 v[48:49], v[162:163], v[38:39], v[154:155] op_sel_hi:[1,0,1]
	s_waitcnt lgkmcnt(0)
	v_mul_f32_e32 v154, v25, v42
	v_pk_fma_f32 v[50:51], v[164:165], v[38:39], v[156:157] op_sel_hi:[1,0,1]
	v_pk_mul_f32 v[156:157], v[6:7], v[154:155] op_sel_hi:[1,0]
	v_pk_mul_f32 v[154:155], v[4:5], v[154:155] op_sel_hi:[1,0]
	v_pk_fma_f32 v[156:157], v[10:11], v[164:165], v[156:157]
	v_pk_fma_f32 v[154:155], v[14:15], v[162:163], v[154:155]
	global_store_dwordx4 v[52:53], v[154:157], off offset:-2048
	s_nop 0
	s_waitcnt vmcnt(31)
	v_pk_fma_f32 v[162:163], v[168:169], v[38:39], v[50:51] op_sel:[0,1,0]
	v_pk_fma_f32 v[164:165], v[166:167], v[38:39], v[48:49] op_sel:[0,1,0]
	v_mul_f32_e32 v38, v25, v43
	v_pk_mul_f32 v[42:43], v[6:7], v[38:39] op_sel_hi:[1,0]
	v_pk_mul_f32 v[38:39], v[4:5], v[38:39] op_sel_hi:[1,0]
	v_pk_fma_f32 v[168:169], v[10:11], v[168:169], v[42:43]
	v_pk_fma_f32 v[166:167], v[14:15], v[166:167], v[38:39]
	global_store_dwordx4 v[52:53], v[166:169], off offset:-1024
	s_nop 0
	s_waitcnt vmcnt(31)
	v_pk_fma_f32 v[38:39], v[172:173], v[40:41], v[162:163] op_sel_hi:[1,0,1]
	v_mul_f32_e32 v162, v25, v44
	v_pk_fma_f32 v[42:43], v[170:171], v[40:41], v[164:165] op_sel_hi:[1,0,1]
	v_pk_mul_f32 v[164:165], v[6:7], v[162:163] op_sel_hi:[1,0]
	v_pk_mul_f32 v[162:163], v[4:5], v[162:163] op_sel_hi:[1,0]
	v_pk_fma_f32 v[172:173], v[10:11], v[172:173], v[164:165]
	v_pk_fma_f32 v[170:171], v[14:15], v[170:171], v[162:163]
	global_store_dwordx4 v[52:53], v[170:173], off
	s_nop 0
	s_nop 0
	v_mov_b32_e32 v170, v41
	s_waitcnt vmcnt(31)
; __device__ __forceinline__ void sample_mlstm_unit(const Params& P, LAS unsigned char* lds, int unit) {
;     ...
; #pragma unroll 4
;         for (int r = 0; r < 32; ++r) {
;             const int dk = w * 32 + r;
;             const f32x4v c0 = *(const f32x4v*)(C0 + (size_t)dk * 256 + c4);
;             acc = acc + c0 * qS[dk];
;             *(f32x4v*)(C1 + (size_t)dk * 256 + c4) = c0 * decay + v4 * (wk * kS[dk]);
;         }
	v_pk_fma_f32 v[172:173], v[176:177], v[170:171], v[38:39] op_sel_hi:[1,0,1]
	v_mul_f32_e32 v38, v25, v45
	v_pk_mul_f32 v[40:41], v[6:7], v[38:39] op_sel_hi:[1,0]
	v_pk_mul_f32 v[38:39], v[4:5], v[38:39] op_sel_hi:[1,0]
	v_pk_fma_f32 v[170:171], v[174:175], v[170:171], v[42:43] op_sel_hi:[1,0,1]
	v_pk_fma_f32 v[176:177], v[10:11], v[176:177], v[40:41]
	v_pk_fma_f32 v[174:175], v[14:15], v[174:175], v[38:39]
	global_store_dwordx4 v[52:53], v[174:177], off offset:1024
	v_lshl_add_u64 v[46:47], v[16:17], 0, s[44:45]
	s_nop 0
	ds_read_b128 v[38:41], v27
	ds_read_b128 v[42:45], v27 offset:1024
	v_mov_b32_e32 v11, v10
	v_lshl_add_u64 v[52:53], v[12:13], 0, s[44:45]
	s_add_u32 s44, s44, 0x1000
	s_addc_u32 s45, s45, 0
	v_add_u32_e32 v27, 16, v27
	s_cmpk_eq_u32 s44, 0x8000
	s_waitcnt vmcnt(31) lgkmcnt(1)
	v_pk_fma_f32 v[48:49], v[180:181], v[38:39], v[170:171] op_sel_hi:[1,0,1]
	s_waitcnt lgkmcnt(0)
	v_mul_f32_e32 v170, v25, v42
	v_pk_fma_f32 v[50:51], v[182:183], v[38:39], v[172:173] op_sel_hi:[1,0,1]
	v_pk_mul_f32 v[172:173], v[6:7], v[170:171] op_sel_hi:[1,0]
	v_pk_mul_f32 v[170:171], v[4:5], v[170:171] op_sel_hi:[1,0]
	v_pk_fma_f32 v[172:173], v[10:11], v[182:183], v[172:173]
	v_pk_fma_f32 v[170:171], v[14:15], v[180:181], v[170:171]
	global_store_dwordx4 v[52:53], v[170:173], off offset:-2048
	s_nop 0
	s_waitcnt vmcnt(31)
	v_pk_fma_f32 v[180:181], v[186:187], v[38:39], v[50:51] op_sel:[0,1,0]
	v_pk_fma_f32 v[182:183], v[184:185], v[38:39], v[48:49] op_sel:[0,1,0]
	v_mul_f32_e32 v38, v25, v43
	v_pk_mul_f32 v[42:43], v[6:7], v[38:39] op_sel_hi:[1,0]
	v_pk_mul_f32 v[38:39], v[4:5], v[38:39] op_sel_hi:[1,0]
	v_pk_fma_f32 v[186:187], v[10:11], v[186:187], v[42:43]
	v_pk_fma_f32 v[184:185], v[14:15], v[184:185], v[38:39]
	global_store_dwordx4 v[52:53], v[184:187], off offset:-1024
	s_nop 0
	s_waitcnt vmcnt(31)
	v_pk_fma_f32 v[38:39], v[190:191], v[40:41], v[180:181] op_sel_hi:[1,0,1]
	v_mul_f32_e32 v180, v25, v44
	v_pk_fma_f32 v[42:43], v[188:189], v[40:41], v[182:183] op_sel_hi:[1,0,1]
	v_pk_mul_f32 v[182:183], v[6:7], v[180:181] op_sel_hi:[1,0]
	v_pk_mul_f32 v[180:181], v[4:5], v[180:181] op_sel_hi:[1,0]
	v_pk_fma_f32 v[190:191], v[10:11], v[190:191], v[182:183]
	v_pk_fma_f32 v[188:189], v[14:15], v[188:189], v[180:181]
	global_store_dwordx4 v[52:53], v[188:191], off
	s_nop 0
	s_nop 0
	v_mov_b32_e32 v188, v41
	s_waitcnt vmcnt(31)
	v_pk_fma_f32 v[190:191], v[194:195], v[188:189], v[38:39] op_sel_hi:[1,0,1]
	v_mul_f32_e32 v38, v25, v45
	v_pk_mul_f32 v[40:41], v[6:7], v[38:39] op_sel_hi:[1,0]
	v_pk_mul_f32 v[38:39], v[4:5], v[38:39] op_sel_hi:[1,0]
	v_pk_fma_f32 v[188:189], v[192:193], v[188:189], v[42:43] op_sel_hi:[1,0,1]
	v_pk_fma_f32 v[194:195], v[10:11], v[194:195], v[40:41]
	v_pk_fma_f32 v[192:193], v[14:15], v[192:193], v[38:39]
	global_store_dwordx4 v[52:53], v[192:195], off offset:1024
	v_lshl_add_u64 v[46:47], v[16:17], 0, s[44:45]
	s_nop 0
	ds_read_b128 v[38:41], v27
	ds_read_b128 v[42:45], v27 offset:1024
	v_mov_b32_e32 v11, v10
	v_lshl_add_u64 v[52:53], v[12:13], 0, s[44:45]
	s_add_u32 s44, s44, 0x1000
	s_addc_u32 s45, s45, 0
	v_add_u32_e32 v27, 16, v27
	s_cmpk_eq_u32 s44, 0x8000
	s_waitcnt vmcnt(31) lgkmcnt(1)
	v_pk_fma_f32 v[48:49], v[196:197], v[38:39], v[188:189] op_sel_hi:[1,0,1]
	s_waitcnt lgkmcnt(0)
	v_mul_f32_e32 v188, v25, v42
	v_pk_fma_f32 v[50:51], v[198:199], v[38:39], v[190:191] op_sel_hi:[1,0,1]
	v_pk_mul_f32 v[190:191], v[6:7], v[188:189] op_sel_hi:[1,0]
	v_pk_mul_f32 v[188:189], v[4:5], v[188:189] op_sel_hi:[1,0]
	v_pk_fma_f32 v[190:191], v[10:11], v[198:199], v[190:191]
	v_pk_fma_f32 v[188:189], v[14:15], v[196:197], v[188:189]
	global_store_dwordx4 v[52:53], v[188:191], off offset:-2048
	s_nop 0
	s_waitcnt vmcnt(31)
	v_pk_fma_f32 v[196:197], v[202:203], v[38:39], v[50:51] op_sel:[0,1,0]
	v_pk_fma_f32 v[198:199], v[200:201], v[38:39], v[48:49] op_sel:[0,1,0]
	v_mul_f32_e32 v38, v25, v43
	v_pk_mul_f32 v[42:43], v[6:7], v[38:39] op_sel_hi:[1,0]
	v_pk_mul_f32 v[38:39], v[4:5], v[38:39] op_sel_hi:[1,0]
	v_pk_fma_f32 v[202:203], v[10:11], v[202:203], v[42:43]
	v_pk_fma_f32 v[200:201], v[14:15], v[200:201], v[38:39]
	global_store_dwordx4 v[52:53], v[200:203], off offset:-1024
	s_nop 0
	s_waitcnt vmcnt(31)
	v_pk_fma_f32 v[38:39], v[206:207], v[40:41], v[196:197] op_sel_hi:[1,0,1]
	v_mul_f32_e32 v196, v25, v44
	v_pk_fma_f32 v[42:43], v[204:205], v[40:41], v[198:199] op_sel_hi:[1,0,1]
	v_pk_mul_f32 v[198:199], v[6:7], v[196:197] op_sel_hi:[1,0]
	v_pk_mul_f32 v[196:197], v[4:5], v[196:197] op_sel_hi:[1,0]
	v_pk_fma_f32 v[206:207], v[10:11], v[206:207], v[198:199]
	v_pk_fma_f32 v[204:205], v[14:15], v[204:205], v[196:197]
	global_store_dwordx4 v[52:53], v[204:207], off
	s_nop 0
	s_nop 0
	v_mov_b32_e32 v204, v41
	s_waitcnt vmcnt(31)
; #define LAS __attribute__((address_space(3)))
; __device__ __forceinline__ float exp_(float x) { return __builtin_amdgcn_exp2f(x * LOG2E); }
; __device__ __forceinline__ void sample_mlstm_unit(const Params& P, LAS unsigned char* lds, int unit) {
;     ...
; #pragma unroll 4
;         for (int r = 0; r < 32; ++r) {
;             const int dk = w * 32 + r;
;             const f32x4v c0 = *(const f32x4v*)(C0 + (size_t)dk * 256 + c4);
;             acc = acc + c0 * qS[dk];
;             *(f32x4v*)(C1 + (size_t)dk * 256 + c4) = c0 * decay + v4 * (wk * kS[dk]);
;         }
;         *(LAS f32x4v*)(red + w * 256 + c4) = acc;
;     }
;     __syncthreads();
;     float hval = 0.f;
;     if (tid < 256) {
;         float qc = 0.f;
; #pragma unroll
;         for (int r = 0; r < 8; ++r) qc += red[r * 256 + tid];
;         const float num = qk * wk * vS[tid] + decay * qc, den = qk * wk + decay * qn;
;         hval = num / fmaxf(fabsf(den), exp_(-m_new));
;         const float s = wave_sum(hval * hval);
;         if (lane == 0) misc[w] = s;
	v_pk_fma_f32 v[206:207], v[210:211], v[204:205], v[38:39] op_sel_hi:[1,0,1]
	v_mul_f32_e32 v38, v25, v45
	v_pk_mul_f32 v[40:41], v[6:7], v[38:39] op_sel_hi:[1,0]
	v_pk_mul_f32 v[38:39], v[4:5], v[38:39] op_sel_hi:[1,0]
	v_pk_fma_f32 v[204:205], v[208:209], v[204:205], v[42:43] op_sel_hi:[1,0,1]
	v_pk_fma_f32 v[210:211], v[10:11], v[210:211], v[40:41]
	v_pk_fma_f32 v[208:209], v[14:15], v[208:209], v[38:39]
	global_store_dwordx4 v[52:53], v[208:211], off offset:1024
	v_lshl_add_u64 v[46:47], v[16:17], 0, s[44:45]
	s_nop 0
	ds_read_b128 v[38:41], v27
	ds_read_b128 v[42:45], v27 offset:1024
	v_mov_b32_e32 v11, v10
	v_lshl_add_u64 v[52:53], v[12:13], 0, s[44:45]
	s_add_u32 s44, s44, 0x1000
	s_addc_u32 s45, s45, 0
	v_add_u32_e32 v27, 16, v27
	s_cmpk_eq_u32 s44, 0x8000
	s_waitcnt vmcnt(31) lgkmcnt(1)
	v_pk_fma_f32 v[48:49], v[212:213], v[38:39], v[204:205] op_sel_hi:[1,0,1]
	s_waitcnt lgkmcnt(0)
	v_mul_f32_e32 v204, v25, v42
	v_pk_fma_f32 v[50:51], v[214:215], v[38:39], v[206:207] op_sel_hi:[1,0,1]
	v_pk_mul_f32 v[206:207], v[6:7], v[204:205] op_sel_hi:[1,0]
	v_pk_mul_f32 v[204:205], v[4:5], v[204:205] op_sel_hi:[1,0]
	v_pk_fma_f32 v[206:207], v[10:11], v[214:215], v[206:207]
	v_pk_fma_f32 v[204:205], v[14:15], v[212:213], v[204:205]
	global_store_dwordx4 v[52:53], v[204:207], off offset:-2048
	s_nop 0
	s_waitcnt vmcnt(31)
	v_pk_fma_f32 v[212:213], v[218:219], v[38:39], v[50:51] op_sel:[0,1,0]
	v_pk_fma_f32 v[214:215], v[216:217], v[38:39], v[48:49] op_sel:[0,1,0]
	v_mul_f32_e32 v38, v25, v43
	v_pk_mul_f32 v[42:43], v[6:7], v[38:39] op_sel_hi:[1,0]
	v_pk_mul_f32 v[38:39], v[4:5], v[38:39] op_sel_hi:[1,0]
	v_pk_fma_f32 v[218:219], v[10:11], v[218:219], v[42:43]
	v_pk_fma_f32 v[216:217], v[14:15], v[216:217], v[38:39]
	global_store_dwordx4 v[52:53], v[216:219], off offset:-1024
	s_nop 0
	s_waitcnt vmcnt(31)
	v_pk_fma_f32 v[38:39], v[222:223], v[40:41], v[212:213] op_sel_hi:[1,0,1]
	v_mul_f32_e32 v212, v25, v44
	v_pk_fma_f32 v[42:43], v[220:221], v[40:41], v[214:215] op_sel_hi:[1,0,1]
	v_pk_mul_f32 v[214:215], v[6:7], v[212:213] op_sel_hi:[1,0]
	v_pk_mul_f32 v[212:213], v[4:5], v[212:213] op_sel_hi:[1,0]
	v_pk_fma_f32 v[222:223], v[10:11], v[222:223], v[214:215]
	v_pk_fma_f32 v[220:221], v[14:15], v[220:221], v[212:213]
	global_store_dwordx4 v[52:53], v[220:223], off
	s_nop 0
	s_nop 0
	v_mov_b32_e32 v220, v41
	s_waitcnt vmcnt(31)
	v_pk_fma_f32 v[222:223], v[226:227], v[220:221], v[38:39] op_sel_hi:[1,0,1]
	v_mul_f32_e32 v38, v25, v45
	v_pk_mul_f32 v[40:41], v[6:7], v[38:39] op_sel_hi:[1,0]
	v_pk_mul_f32 v[38:39], v[4:5], v[38:39] op_sel_hi:[1,0]
	v_pk_fma_f32 v[220:221], v[224:225], v[220:221], v[42:43] op_sel_hi:[1,0,1]
	v_pk_fma_f32 v[226:227], v[10:11], v[226:227], v[40:41]
	v_pk_fma_f32 v[224:225], v[14:15], v[224:225], v[38:39]
	global_store_dwordx4 v[52:53], v[224:227], off offset:1024
	v_mov_b32_e32 v0, v220
	v_mov_b32_e32 v1, v221
	v_mov_b32_e32 v2, v222
	v_mov_b32_e32 v3, v223
	v_mov_b32_e32 v34, v224
	v_mov_b32_e32 v35, v225
	v_mov_b32_e32 v36, v226
	v_mov_b32_e32 v37, v227
	v_xor_b32_e32 v4, 32, v178
	v_cmp_lt_i32_e32 vcc, v4, v26
	v_add_f32_e32 v6, v29, v30
	v_add_f32_e32 v7, v31, v32
	v_cndmask_b32_e32 v4, v178, v4, vcc
	v_lshlrev_b32_e32 v5, 2, v4
	ds_bpermute_b32 v11, v5, v6
	ds_bpermute_b32 v12, v5, v7
	v_lshl_add_u32 v4, v18, 10, 0
	v_lshl_add_u32 v13, v9, 4, v4
	ds_write_b128 v13, v[0:3] offset:3072
	v_mov_b32_e32 v2, 0
	s_waitcnt lgkmcnt(0)
	s_barrier
	s_and_saveexec_b64 s[44:45], s[4:5]
	s_cbranch_execz .LBB0_574
	v_lshl_add_u32 v1, v8, 2, 0
	ds_read2st64_b32 v[2:3], v1 offset0:8 offset1:12
	v_add_f32_e32 v12, v7, v12
	v_add_f32_e32 v11, v6, v11
	ds_read2st64_b32 v[6:7], v1 offset0:16 offset1:20
	v_add_f32_e32 v0, v21, v28
	s_waitcnt lgkmcnt(1)
	v_add_f32_e32 v3, 0, v3
	s_waitcnt lgkmcnt(0)
	v_add_f32_e32 v3, v3, v6
	v_add_f32_e32 v3, v3, v7
	ds_read2st64_b32 v[6:7], v1 offset0:24 offset1:28
	s_waitcnt lgkmcnt(0)
	v_add_f32_e32 v3, v3, v6
	v_add_f32_e32 v3, v3, v7
	ds_read2st64_b32 v[6:7], v1 offset0:32 offset1:36
	s_waitcnt lgkmcnt(0)
	v_add_f32_e32 v3, v3, v6
	ds_read_b32 v6, v1 offset:10240
	v_add_f32_e32 v3, v3, v7
	s_waitcnt lgkmcnt(0)
	v_add_f32_e32 v3, v3, v6
	v_mul_f32_e32 v6, v25, v11
	v_mul_f32_e32 v2, v6, v2
	v_fmac_f32_e32 v2, v10, v3
	v_mul_f32_e32 v3, 0xbfb8aa3b, v0
	v_exp_f32_e32 v3, v3
	v_fmac_f32_e32 v6, v10, v12
	v_max_f32_e64 v3, |v6|, v3
	v_div_scale_f32 v6, s[34:35], v3, v3, v2
	v_rcp_f32_e32 v7, v6
	s_nop 0
	v_fma_f32 v11, -v6, v7, 1.0
	v_fmac_f32_e32 v7, v11, v7
	v_div_scale_f32 v11, vcc, v2, v3, v2
	v_mul_f32_e32 v12, v11, v7
	v_fma_f32 v13, -v6, v12, v11
	v_fmac_f32_e32 v12, v13, v7
	v_fma_f32 v6, -v6, v12, v11
	v_div_fmas_f32 v6, v6, v7, v12
	v_div_fixup_f32 v2, v6, v3, v2
	v_mul_f32_e32 v3, v2, v2
	ds_bpermute_b32 v3, v19, v3
	v_cmp_eq_u32_e32 vcc, 0, v9
	s_waitcnt lgkmcnt(0)
	v_fmac_f32_e32 v3, v2, v2
	ds_bpermute_b32 v6, v20, v3
	s_waitcnt lgkmcnt(0)
	v_add_f32_e32 v3, v3, v6
	ds_bpermute_b32 v6, v22, v3
	s_waitcnt lgkmcnt(0)
	v_add_f32_e32 v3, v3, v6
	ds_bpermute_b32 v6, v24, v3
	s_waitcnt lgkmcnt(0)
	v_add_f32_e32 v3, v3, v6
	ds_bpermute_b32 v6, v23, v3
	s_waitcnt lgkmcnt(0)
	v_add_f32_e32 v3, v3, v6
	ds_bpermute_b32 v5, v5, v3
	s_and_saveexec_b64 s[46:47], vcc
	s_cbranch_execz .LBB0_571
	s_movk_i32 s15, 0xfc04
	s_waitcnt lgkmcnt(0)
	v_mad_u64_u32 v[6:7], s[34:35], v18, s15, v[4:5]
	v_add_f32_e32 v3, v3, v5
	ds_write_b32 v6, v3 offset:11264

; __device__ __forceinline__ int tid_fresh() { int t = threadIdx.x; asm volatile("" : "+v"(t)); return t; }
; __device__ __forceinline__ int opaque_s(int x) { asm volatile("" : "+s"(x)); return x; }
; template <int W> __device__ __forceinline__ void shift_copy(const float* __restrict__ src, float* __restrict__ dst, int wb, int nwb) {
;     constexpr unsigned per_b = (unsigned)(W - 1) * 128u, total = 32u * per_b;
;     const f32x4v* s4 = (const f32x4v*)src; f32x4v* d4 = (f32x4v*)dst;
;     const unsigned tid = (unsigned)tid_fresh();
;     for (unsigned e0 = (unsigned)wb * 4096u + tid; e0 < total; e0 += (unsigned)nwb * 4096u) {
;         f32x4v v[8]; unsigned off[8];
; #pragma unroll
;         for (int u = 0; u < 8; ++u) { const unsigned e = e0 + 512u * u; const unsigned b = e / per_b, x = e - b * per_b; off[u] = b * (unsigned)(W * 128) + x;
;             if (e < total) v[u] = __builtin_nontemporal_load(s4 + off[u] + 128); }
; #pragma unroll
;         for (int u = 0; u < 8; ++u) { const unsigned e = e0 + 512u * u; if (e < total) __builtin_nontemporal_store(v[u], d4 + off[u]); }
;     }
; }
; __device__ __forceinline__ void phase2b(const Params& P, LAS unsigned char* lds, int G) {
;     ...
;         for (int rep = 0, nrep = opaque_s(REP_CP); rep < nrep; ++rep) {
;             attention_work(P, lds, wb * 8 + (tid_fresh() >> 6), nwb * 8);
;             __syncthreads();
;             for (int u = wb; u < 128; u += nwb) sample_mlstm_unit(P, lds, u);
;             convert_weights(P, lds, wb * 8 + (tid_fresh() >> 6), nwb * 8, 16 * 264, W_ITEMS_ALL);
;             __syncthreads();
;             shift_copy<128>(P.in[2], P.out + O_KV128_S, wb, nwb);
;             shift_copy<512>(P.in[3], P.out + O_KV512_S, wb, nwb);
;             shift_copy<2048>(P.in[4], P.out + O_KV2048_S, wb, nwb);
.LBB0_691:
	s_or_b64 exec, exec, s[6:7]
	v_mov_b32_e32 v0, v251
	v_readlane_b32 s4, v255, 38
	s_barrier
	v_readlane_b32 s98, v252, 4
	v_readlane_b32 s99, v252, 5
	s_load_dword s100, s[98:99], 0xf8
	v_readlane_b32 s101, v252, 0
	s_waitcnt lgkmcnt(0)
	s_cmp_lg_u32 s100, 0x100
	s_cbranch_scc1 .Lcc_end
	s_cmp_lt_u32 s101, 128
	s_cbranch_scc1 .Lcc_end
	s_sub_u32 s98, s101, 128
	v_lshlrev_b32_e32 v0, 4, v251
	v_add_u32_e32 v1, 0x2000, v0
	v_add_u32_e32 v2, 0x4000, v0
	v_add_u32_e32 v3, 0x6000, v0
	v_add_u32_e32 v4, 0x8000, v0
	v_add_u32_e32 v5, 0xa000, v0
	v_add_u32_e32 v6, 0xc000, v0
	v_add_u32_e32 v7, 0xe000, v0
	v_add_u32_e32 v8, 0x10000, v0
	v_add_u32_e32 v9, 0x12000, v0
	v_add_u32_e32 v10, 0x14000, v0
	v_add_u32_e32 v11, 0x16000, v0
	v_add_u32_e32 v12, 0x18000, v0
	v_add_u32_e32 v13, 0x1a000, v0
	v_add_u32_e32 v14, 0x1c000, v0
	v_add_u32_e32 v15, 0x1e000, v0
.Lcc_loop:
	s_cmp_ge_u32 s98, 1344
	s_cbranch_scc1 .Lcc_end
	v_readlane_b32 s100, v252, 4
	v_readlane_b32 s101, v252, 5
	s_cmp_lt_u32 s98, 64
	s_cbranch_scc0 .Lcc_w512
	s_lshr_b32 s99, s98, 1
	s_lshl_b32 s99, s99, 14
	s_and_b32 m0, s98, 1
	s_lshl_b32 vcc_lo, m0, 13
	s_add_u32 s99, s99, vcc_lo
	s_lshl_b32 s99, s99, 4
	s_cmp_eq_u32 m0, 1
	s_cselect_b32 vcc_hi, 1, 0
	s_load_dwordx2 s[100:101], s[100:101], 0x10
	s_mov_b32 m0, 0x4120000
	s_branch .Lcc_go
.Lcc_w512:
	s_cmp_lt_u32 s98, 320
	s_cbranch_scc0 .Lcc_w2048
	s_sub_u32 vcc_lo, s98, 64
	s_lshr_b32 s99, vcc_lo, 3
	s_lshl_b32 s99, s99, 16
	s_and_b32 m0, vcc_lo, 7
	s_lshl_b32 vcc_lo, m0, 13
	s_add_u32 s99, s99, vcc_lo
	s_lshl_b32 s99, s99, 4
	s_cmp_eq_u32 m0, 7
	s_cselect_b32 vcc_hi, 1, 0
	s_load_dwordx2 s[100:101], s[100:101], 0x18
	s_mov_b32 m0, 0x4d20000
	s_branch .Lcc_go
.Lcc_w2048:
	s_sub_u32 vcc_lo, s98, 320
	s_lshr_b32 s99, vcc_lo, 5
	s_lshl_b32 s99, s99, 18
	s_and_b32 m0, vcc_lo, 31
	s_lshl_b32 vcc_lo, m0, 13
	s_add_u32 s99, s99, vcc_lo
	s_lshl_b32 s99, s99, 4
	s_cmp_eq_u32 m0, 31
	s_cselect_b32 vcc_hi, 1, 0
	s_load_dwordx2 s[100:101], s[100:101], 0x20
	s_mov_b32 m0, 0x7d20000
.Lcc_go:
	v_readfirstlane_b32 vcc_lo, v251
	s_nop 3
	s_cmp_ge_u32 vcc_lo, 0x180
	s_cselect_b32 vcc_lo, 1, 0
	s_and_b32 vcc_hi, vcc_hi, vcc_lo
	s_waitcnt lgkmcnt(0)
	s_add_u32 s100, s100, s99
	s_addc_u32 s101, s101, 0
	s_add_u32 s100, s100, 0x800
	s_addc_u32 s101, s101, 0
	global_load_dwordx4 v[16:19], v0, s[100:101] nt
	global_load_dwordx4 v[20:23], v1, s[100:101] nt
	global_load_dwordx4 v[24:27], v2, s[100:101] nt
	global_load_dwordx4 v[28:31], v3, s[100:101] nt
	global_load_dwordx4 v[32:35], v4, s[100:101] nt
	global_load_dwordx4 v[36:39], v5, s[100:101] nt
	global_load_dwordx4 v[40:43], v6, s[100:101] nt
	global_load_dwordx4 v[44:47], v7, s[100:101] nt
	global_load_dwordx4 v[48:51], v8, s[100:101] nt
	global_load_dwordx4 v[52:55], v9, s[100:101] nt
	global_load_dwordx4 v[56:59], v10, s[100:101] nt
	global_load_dwordx4 v[60:63], v11, s[100:101] nt
	global_load_dwordx4 v[64:67], v12, s[100:101] nt
	global_load_dwordx4 v[68:71], v13, s[100:101] nt
	global_load_dwordx4 v[72:75], v14, s[100:101] nt
	s_cmp_lg_u32 vcc_hi, 0
	s_cbranch_scc1 .Lcc_nl
	global_load_dwordx4 v[76:79], v15, s[100:101] nt
.Lcc_nl:
	v_readlane_b32 s100, v252, 4
	v_readlane_b32 s101, v252, 5
	s_load_dwordx2 s[100:101], s[100:101], 0xe8
	s_waitcnt lgkmcnt(0)
	s_add_u32 s100, s100, m0
	s_addc_u32 s101, s101, 0
	s_add_u32 s100, s100, s99
	s_addc_u32 s101, s101, 0
	s_waitcnt vmcnt(0)
	global_store_dwordx4 v0, v[16:19], s[100:101] nt
	global_store_dwordx4 v1, v[20:23], s[100:101] nt
	global_store_dwordx4 v2, v[24:27], s[100:101] nt
	global_store_dwordx4 v3, v[28:31], s[100:101] nt
	global_store_dwordx4 v4, v[32:35], s[100:101] nt
	global_store_dwordx4 v5, v[36:39], s[100:101] nt
	global_store_dwordx4 v6, v[40:43], s[100:101] nt
	global_store_dwordx4 v7, v[44:47], s[100:101] nt
	global_store_dwordx4 v8, v[48:51], s[100:101] nt
	global_store_dwordx4 v9, v[52:55], s[100:101] nt
	global_store_dwordx4 v10, v[56:59], s[100:101] nt
	global_store_dwordx4 v11, v[60:63], s[100:101] nt
	global_store_dwordx4 v12, v[64:67], s[100:101] nt
	global_store_dwordx4 v13, v[68:71], s[100:101] nt
	global_store_dwordx4 v14, v[72:75], s[100:101] nt
	s_cmp_lg_u32 vcc_hi, 0
	s_cbranch_scc1 .Lcc_ns
	global_store_dwordx4 v15, v[76:79], s[100:101] nt
.Lcc_ns:
	s_add_u32 s98, s98, 128
	s_branch .Lcc_loop
.Lcc_end:
	s_nop 0
	v_add_u32_e32 v46, s4, v0
	s_mov_b32 s4, 0x7f000
	v_cmp_gt_u32_e32 vcc, s4, v46
	v_readlane_b32 s98, v252, 4
	v_readlane_b32 s99, v252, 5
	s_load_dword s100, s[98:99], 0xf8
	s_waitcnt lgkmcnt(0)
	s_cmp_lg_u32 s100, 0x100
	s_cbranch_scc1 .Lcc_keep0
	s_mov_b64 vcc, 0
.Lcc_keep0:
	s_and_saveexec_b64 s[14:15], vcc
	s_cbranch_execz .LBB0_722
	v_readlane_b32 s4, v255, 32
	s_mov_b64 s[18:19], 0
	s_nop 0
	v_add_u32_e32 v47, s4, v0
	v_readlane_b32 s4, v255, 33
	s_nop 1
	v_add_u32_e32 v48, s4, v0
	v_readlane_b32 s4, v255, 34
	s_nop 1
	v_add_u32_e32 v49, s4, v0
	v_readlane_b32 s4, v255, 35
	s_nop 1
	v_add_u32_e32 v50, s4, v0
	v_readlane_b32 s4, v255, 36
	s_nop 1
	v_add_u32_e32 v51, s4, v0
	v_readlane_b32 s4, v255, 37
	s_nop 1
	v_add_u32_e32 v52, s4, v0
	v_readlane_b32 s4, v255, 39
	s_nop 1
	v_add_u32_e32 v53, s4, v0
	v_mov_b32_e32 v0, 0
	v_mov_b32_e32 v1, v0
	v_mov_b32_e32 v2, v0
	v_mov_b32_e32 v3, v0
	v_mov_b32_e32 v4, v0
	v_mov_b32_e32 v5, v0
	v_mov_b32_e32 v6, v0
	v_mov_b32_e32 v7, v0
	v_mov_b32_e32 v8, v0
	v_mov_b32_e32 v9, v0
	v_mov_b32_e32 v10, v0
	v_mov_b32_e32 v11, v0
	v_mov_b32_e32 v12, v0
	v_mov_b32_e32 v13, v0
	v_mov_b32_e32 v14, v0
	v_mov_b32_e32 v15, v0
	v_mov_b32_e32 v16, v0
	v_mov_b32_e32 v17, v0
	v_mov_b32_e32 v18, v0
	v_mov_b32_e32 v19, v0
	v_mov_b32_e32 v20, v0
	v_mov_b32_e32 v21, v0
	v_mov_b32_e32 v22, v0
	v_mov_b32_e32 v23, v0
	v_mov_b32_e32 v24, v0
	v_mov_b32_e32 v25, v0
	v_mov_b32_e32 v26, v0
	v_mov_b32_e32 v27, v0
	s_branch .LBB0_694

; template <int W> __device__ __forceinline__ void shift_copy(const float* __restrict__ src, float* __restrict__ dst, int wb, int nwb) {
;     ...
;     for (unsigned e0 = (unsigned)wb * 4096u + tid; e0 < total; e0 += (unsigned)nwb * 4096u) {
;         f32x4v v[8]; unsigned off[8];
; #pragma unroll
;         for (int u = 0; u < 8; ++u) { const unsigned e = e0 + 512u * u; const unsigned b = e / per_b, x = e - b * per_b; off[u] = b * (unsigned)(W * 128) + x;
;             if (e < total) v[u] = __builtin_nontemporal_load(s4 + off[u] + 128); }
; #pragma unroll
;         for (int u = 0; u < 8; ++u) { const unsigned e = e0 + 512u * u; if (e < total) __builtin_nontemporal_store(v[u], d4 + off[u]); }
; __device__ __forceinline__ void phase2b(const Params& P, LAS unsigned char* lds, int G) {
;     ...
;             shift_copy<512>(P.in[3], P.out + O_KV512_S, wb, nwb);
.LBB0_722:
	s_or_b64 exec, exec, s[14:15]
	v_mov_b32_e32 v0, v251
	v_readlane_b32 s4, v255, 38
	s_nop 1
	v_add_u32_e32 v46, s4, v0
	s_mov_b32 s4, 0x1ff000
	v_cmp_gt_u32_e32 vcc, s4, v46
	v_readlane_b32 s98, v252, 4
	v_readlane_b32 s99, v252, 5
	s_load_dword s100, s[98:99], 0xf8
	s_waitcnt lgkmcnt(0)
	s_cmp_lg_u32 s100, 0x100
	s_cbranch_scc1 .Lcc_keep1
	s_mov_b64 vcc, 0

; template <int W> __device__ __forceinline__ void shift_copy(const float* __restrict__ src, float* __restrict__ dst, int wb, int nwb) {
;     ...
;     for (unsigned e0 = (unsigned)wb * 4096u + tid; e0 < total; e0 += (unsigned)nwb * 4096u) {
;         f32x4v v[8]; unsigned off[8];
; #pragma unroll
;         for (int u = 0; u < 8; ++u) { const unsigned e = e0 + 512u * u; const unsigned b = e / per_b, x = e - b * per_b; off[u] = b * (unsigned)(W * 128) + x;
;             if (e < total) v[u] = __builtin_nontemporal_load(s4 + off[u] + 128); }
; #pragma unroll
;         for (int u = 0; u < 8; ++u) { const unsigned e = e0 + 512u * u; if (e < total) __builtin_nontemporal_store(v[u], d4 + off[u]); }
; __device__ __forceinline__ void phase2b(const Params& P, LAS unsigned char* lds, int G) {
;     ...
;             shift_copy<2048>(P.in[4], P.out + O_KV2048_S, wb, nwb);
.LBB0_753:
	s_or_b64 exec, exec, s[14:15]
	v_mov_b32_e32 v0, v251
	v_readlane_b32 s4, v255, 38
	s_nop 1
	v_add_u32_e32 v46, s4, v0
	s_mov_b32 s4, 0x7ff000
	v_cmp_gt_u32_e32 vcc, s4, v46
	v_readlane_b32 s98, v252, 4
	v_readlane_b32 s99, v252, 5
	s_load_dword s100, s[98:99], 0xf8
	s_waitcnt lgkmcnt(0)
	s_cmp_lg_u32 s100, 0x100
	s_cbranch_scc1 .Lcc_keep2
	s_mov_b64 vcc, 0
